# attention softmax: packed f32 fma / add in the generated loop
# baseline (speedup 1.0000x reference)
.LBB0_1098:
	s_xor_b64 s[30:31], s[0:1], -1
	s_and_b64 s[0:1], s[0:1], exec
	s_cselect_b32 s1, s19, s37
	v_mov_b32_e32 v174, v190
	s_lshl_b32 s14, s1, 15
	s_lshl_b32 s0, s1, 16
	s_add_u32 s4, s16, s0
	v_readfirstlane_b32 s7, v174
	s_addc_u32 s5, s17, 0
	s_ashr_i32 s0, s7, 6
	v_lshlrev_b32_e32 v1, 3, v174
	s_lshl_b32 s6, s1, 8
	s_lshl_b32 s38, s1, 2
	s_ashr_i32 s1, s0, 31
	v_ashrrev_i32_e32 v0, 4, v174
	v_and_b32_e32 v2, 0x78, v1
	v_and_b32_e32 v175, 31, v174
	v_bfe_u32 v176, v174, 5, 1
	s_lshl_b32 s39, s0, 5
	s_and_b32 s7, s7, 0x3fffffc0
	s_lshl_b64 s[28:29], s[0:1], 13
	v_lshlrev_b32_e32 v2, 1, v2
	v_lshlrev_b32_e32 v3, 8, v0
	v_lshlrev_b32_e32 v10, 8, v175
	v_lshlrev_b32_e32 v11, 4, v176
	s_add_u32 s0, s4, s28
	v_or_b32_e32 v148, v2, v3
	v_or_b32_e32 v12, v11, v10
	s_addc_u32 s1, s5, s29
	global_load_dwordx4 v[96:99], v148, s[22:23]
	global_load_dwordx4 v[100:103], v148, s[20:21]
	global_load_dwordx4 v[136:139], v148, s[42:43]
	global_load_dwordx4 v[140:143], v148, s[26:27]
	global_load_dwordx4 v[104:107], v12, s[0:1]
	global_load_dwordx4 v[108:111], v12, s[0:1] offset:32
	global_load_dwordx4 v[112:115], v12, s[0:1] offset:64
	global_load_dwordx4 v[116:119], v12, s[0:1] offset:96
	global_load_dwordx4 v[120:123], v12, s[0:1] offset:128
	global_load_dwordx4 v[124:127], v12, s[0:1] offset:160
	global_load_dwordx4 v[128:131], v12, s[0:1] offset:192
	global_load_dwordx4 v[132:135], v12, s[0:1] offset:224
	v_and_b32_e32 v6, 0xfffff0, v0
	v_lshlrev_b32_e32 v7, 1, v0
	v_and_or_b32 v6, v7, 8, v6
	v_lshrrev_b32_e32 v7, 1, v0
	v_and_b32_e32 v8, 3, v0
	v_add_u32_e32 v0, 32, v0
	v_and_b32_e32 v4, 63, v174
	v_and_b32_e32 v9, 0xfffff0, v0
	v_lshlrev_b32_e32 v0, 1, v0
	v_lshlrev_b32_e32 v12, 4, v174
	s_lshl_b32 s0, s7, 2
	v_and_or_b32 v0, v0, 8, v9
	v_lshlrev_b32_e32 v9, 3, v4
	v_and_b32_e32 v13, 0xc0, v12
	v_lshlrev_b32_e32 v14, 1, v174
	s_add_i32 s0, s0, 0
	v_lshlrev_b32_e32 v5, 2, v176
	v_and_or_b32 v13, v9, 24, v13
	v_and_b32_e32 v14, 32, v14
	v_and_b32_e32 v9, 0x100, v9
	s_add_i32 s18, s38, 4
	s_add_i32 s39, s39, s6
	s_add_i32 s4, s0, 0x10000
	v_lshrrev_b32_e32 v6, 1, v6
	v_bfe_u32 v1, v1, 5, 2
	v_lshrrev_b32_e32 v0, 1, v0
	v_or3_b32 v9, v13, v14, v9
	v_subrev_u32_e32 v13, s6, v5
	s_cmp_lg_u32 0, -1
	v_or_b32_e32 v6, v6, v1
	v_and_or_b32 v7, v7, 4, v8
	v_or_b32_e32 v0, v0, v1
	v_and_b32_e32 v1, 0x70, v174
	v_cvt_f32_i32_e32 v13, v13
	s_cselect_b32 s0, 0, 0
	v_lshlrev_b32_e32 v6, 9, v6
	v_lshlrev_b32_e32 v7, 6, v7
	v_and_b32_e32 v8, 48, v2
	v_lshlrev_b32_e32 v0, 9, v0
	v_bitop3_b32 v1, v2, v3, v1 bitop3:0xde
	v_add_u32_e32 v178, s0, v9
	s_movk_i32 s0, 0x70
	v_or3_b32 v0, v0, v7, v8
	v_or3_b32 v6, v6, v7, v8
	v_add_u32_e32 v182, 0, v1
	v_and_b32_e32 v1, 0x70, v12
	v_bitop3_b32 v2, v11, v12, s0 bitop3:0x78
	s_movk_i32 s0, 0x60
	s_waitcnt vmcnt(0)
	v_add_u32_e32 v180, 0, v6
	v_add_u32_e32 v181, 0, v0
	v_add_u32_e32 v0, 0, v10
	v_bitop3_b32 v3, v11, v1, 32 bitop3:0x36
	v_bitop3_b32 v6, v11, v1, 64 bitop3:0x36
	v_bitop3_b32 v1, v11, v1, s0 bitop3:0x36
	v_cmp_gt_u32_e64 s[0:1], 32, v4
	v_or_b32_e32 v4, s39, v175
	v_mov_b32_e32 v32, v149
	v_mov_b32_e32 v33, v149
	v_mov_b32_e32 v46, v149
	v_mov_b32_e32 v47, v149
	v_mul_f32_e32 v179, v172, v13
	v_add_u32_e32 v177, s4, v11
	v_sub_u32_e32 v184, v4, v5
	v_mov_b32_e32 v34, v149
	v_mov_b32_e32 v35, v149
	v_mov_b32_e32 v36, v149
	v_mov_b32_e32 v37, v149
	v_mov_b32_e32 v38, v149
	v_mov_b32_e32 v39, v149
	v_mov_b32_e32 v40, v149
	v_mov_b32_e32 v41, v149
	v_mov_b32_e32 v42, v149
	v_mov_b32_e32 v43, v149
	v_mov_b32_e32 v44, v149
	v_mov_b32_e32 v45, v149
	v_add_u32_e32 v186, v0, v2
	v_add_u32_e32 v187, v0, v3
	v_add_u32_e32 v188, v0, v6
	v_add_u32_e32 v189, v0, v1
	v_mov_b64_e32 v[62:63], v[46:47]
	v_mov_b64_e32 v[16:17], v[32:33]
	v_mov_b64_e32 v[0:1], v[32:33]
	s_mov_b32 s12, 0
	v_lshl_add_u32 v183, v175, 2, s4
	v_mov_b32_e32 v203, 0xf149f2ca
	v_mov_b32_e32 v185, 0
	s_movk_i32 s13, 0x7f
	s_mov_b64 s[46:47], s[2:3]
	s_mov_b64 s[40:41], s[24:25]
	v_mov_b64_e32 v[60:61], v[44:45]
	v_mov_b64_e32 v[58:59], v[42:43]
	v_mov_b64_e32 v[56:57], v[40:41]
	v_mov_b64_e32 v[54:55], v[38:39]
	v_mov_b64_e32 v[52:53], v[36:37]
	v_mov_b64_e32 v[50:51], v[34:35]
	v_mov_b64_e32 v[48:49], v[32:33]
	v_mov_b64_e32 v[18:19], v[34:35]
	v_mov_b64_e32 v[20:21], v[36:37]
	v_mov_b64_e32 v[22:23], v[38:39]
	v_mov_b64_e32 v[24:25], v[40:41]
	v_mov_b64_e32 v[26:27], v[42:43]
	v_mov_b64_e32 v[28:29], v[44:45]
	v_mov_b64_e32 v[30:31], v[46:47]
	v_mov_b64_e32 v[2:3], v[34:35]
	v_mov_b64_e32 v[4:5], v[36:37]
	v_mov_b64_e32 v[6:7], v[38:39]
	v_mov_b64_e32 v[8:9], v[40:41]
	v_mov_b64_e32 v[10:11], v[42:43]
	v_mov_b64_e32 v[12:13], v[44:45]
	v_mov_b64_e32 v[14:15], v[46:47]
	s_waitcnt vmcnt(11)
	ds_write_b128 v180, v[96:99]
	s_waitcnt vmcnt(10)
	ds_write_b128 v181, v[100:103]
	s_waitcnt vmcnt(9)
	ds_write_b128 v182, v[136:139] offset:32768
	s_waitcnt vmcnt(8)
	ds_write_b128 v182, v[140:143] offset:40960
	s_waitcnt lgkmcnt(0)
	s_barrier
	v_add_u32_e32 v168, 0x4000, v148
	global_load_dwordx4 v[136:139], v168, s[42:43]
	global_load_dwordx4 v[140:143], v168, s[26:27]
	v_add_u32_e32 v169, 0x4000, v168
	s_mov_b32 s13, 0
	s_mov_b32 s12, 0
	s_mov_b32 s10, 0x3e0293ee
	s_mov_b32 s6, 0x11000
	s_mov_b32 s7, 0
	s_mov_b32 s8, 0x4000
	ds_read_b128 v[236:239], v186 offset:32768
	ds_read_b128 v[240:243], v186 offset:40960
	v_mov_b32_e32 v244, 0
	v_mov_b32_e32 v245, 0
	v_mov_b32_e32 v246, 0
	v_mov_b32_e32 v247, 0
	v_add_u32_e32 v200, s6, v180
	v_add_u32_e32 v201, s6, v181
	ds_write_b128 v200, v[244:247]
	ds_write_b128 v201, v[244:247]
	v_mov_b32_e32 v204, 0
	v_mov_b32_e32 v205, 0
	v_mov_b32_e32 v206, 0
	v_mov_b32_e32 v207, 0
	v_mov_b32_e32 v208, 0
	v_mov_b32_e32 v209, 0
	v_mov_b32_e32 v210, 0
	v_mov_b32_e32 v211, 0
	v_mov_b32_e32 v212, 0
	v_mov_b32_e32 v213, 0
	v_mov_b32_e32 v214, 0
	v_mov_b32_e32 v215, 0
	v_mov_b32_e32 v216, 0
	v_mov_b32_e32 v217, 0
	v_mov_b32_e32 v218, 0
	v_mov_b32_e32 v219, 0
	v_cvt_f32_u32_e32 v64, s13
	v_mov_b32_e32 v165, v164
	v_fma_f32 v64, v172, v64, v179
	v_add_f32_e32 v68, v173, v64
	v_add_f32_e32 v72, v173, v68
	v_add_f32_e32 v76, v173, v72
	v_add_f32_e32 v65, v172, v64
	v_add_f32_e32 v69, v172, v68
	v_add_f32_e32 v73, v172, v72
	v_add_f32_e32 v77, v172, v76
	v_pk_add_f32 v[66:67], v[162:163], v[64:65] op_sel_hi:[1,0]
	v_pk_add_f32 v[70:71], v[162:163], v[68:69] op_sel_hi:[1,0]
	v_pk_add_f32 v[74:75], v[162:163], v[72:73] op_sel_hi:[1,0]
	v_pk_add_f32 v[78:79], v[162:163], v[76:77] op_sel_hi:[1,0]
	v_pk_add_f32 v[82:83], v[164:165], v[66:67]
	v_pk_add_f32 v[80:81], v[166:167], v[64:65]
	v_pk_add_f32 v[86:87], v[164:165], v[70:71]
	v_pk_add_f32 v[84:85], v[164:165], v[68:69]
	v_pk_add_f32 v[90:91], v[164:165], v[74:75]
	v_pk_add_f32 v[88:89], v[164:165], v[72:73]
	v_pk_add_f32 v[94:95], v[164:165], v[78:79]
	v_pk_add_f32 v[92:93], v[164:165], v[76:77]
	s_addk_i32 s13, 0x40
	s_waitcnt lgkmcnt(3)
	v_mfma_f32_32x32x16_bf16 v[64:79], v[236:239], v[104:107], v[64:79]
	ds_read_b128 v[236:239], v187 offset:32768
	s_waitcnt lgkmcnt(3)
	v_mfma_f32_32x32x16_bf16 v[80:95], v[240:243], v[104:107], v[80:95]
	ds_read_b128 v[240:243], v187 offset:40960
	s_waitcnt lgkmcnt(1)
	v_mfma_f32_32x32x16_bf16 v[64:79], v[236:239], v[108:111], v[64:79]
	ds_read_b128 v[236:239], v188 offset:32768
	s_waitcnt lgkmcnt(1)
	v_mfma_f32_32x32x16_bf16 v[80:95], v[240:243], v[108:111], v[80:95]
	ds_read_b128 v[240:243], v188 offset:40960
	s_waitcnt lgkmcnt(1)
	v_mfma_f32_32x32x16_bf16 v[64:79], v[236:239], v[112:115], v[64:79]
	ds_read_b128 v[236:239], v189 offset:32768
	s_waitcnt lgkmcnt(1)
	v_mfma_f32_32x32x16_bf16 v[80:95], v[240:243], v[112:115], v[80:95]
	ds_read_b128 v[240:243], v189 offset:40960
	s_waitcnt lgkmcnt(1)
	v_mfma_f32_32x32x16_bf16 v[64:79], v[236:239], v[116:119], v[64:79]
	ds_read_b128 v[236:239], v186 offset:32896
	s_waitcnt lgkmcnt(1)
	v_mfma_f32_32x32x16_bf16 v[80:95], v[240:243], v[116:119], v[80:95]
	ds_read_b128 v[240:243], v186 offset:41088
	s_waitcnt lgkmcnt(1)
	v_mfma_f32_32x32x16_bf16 v[64:79], v[236:239], v[120:123], v[64:79]
	ds_read_b128 v[236:239], v187 offset:32896
	s_waitcnt lgkmcnt(1)
	v_mfma_f32_32x32x16_bf16 v[80:95], v[240:243], v[120:123], v[80:95]
	ds_read_b128 v[240:243], v187 offset:41088
	s_waitcnt lgkmcnt(1)
	v_mfma_f32_32x32x16_bf16 v[64:79], v[236:239], v[124:127], v[64:79]
	ds_read_b128 v[236:239], v188 offset:32896
	s_waitcnt lgkmcnt(1)
	v_mfma_f32_32x32x16_bf16 v[80:95], v[240:243], v[124:127], v[80:95]
	ds_read_b128 v[240:243], v188 offset:41088
	s_waitcnt lgkmcnt(1)
	v_mfma_f32_32x32x16_bf16 v[64:79], v[236:239], v[128:131], v[64:79]
	ds_read_b128 v[236:239], v189 offset:32896
	s_waitcnt lgkmcnt(1)
	v_mfma_f32_32x32x16_bf16 v[80:95], v[240:243], v[128:131], v[80:95]
	ds_read_b128 v[240:243], v189 offset:41088
	s_waitcnt lgkmcnt(1)
	v_mfma_f32_32x32x16_bf16 v[64:79], v[236:239], v[132:135], v[64:79]
	s_waitcnt lgkmcnt(0)
	v_mfma_f32_32x32x16_bf16 v[80:95], v[240:243], v[132:135], v[80:95]
	s_waitcnt vmcnt(0)
	ds_write_b128 v182, v[136:139] offset:49152
	ds_write_b128 v182, v[140:143] offset:57344
	s_waitcnt lgkmcnt(0)
	s_barrier

.Lat_nme:
	v_add_u32_e32 v184, 0xffffffc0, v184
	v_max_f32_e32 v200, v65, v65
	s_waitcnt lgkmcnt(0)
	v_mfma_f32_32x32x16_bf16 v[32:47], v[204:207], v[220:223], v[32:47]
	ds_read_b64_tr_b16 v[220:221], v165 offset:512
	ds_read_b64_tr_b16 v[222:223], v165 offset:2560
	v_max_f32_e32 v201, v64, v64
	v_max_f32_e32 v200, v201, v200
	v_max3_f32 v200, v200, v66, v67
	v_max3_f32 v200, v200, v68, v69
	v_max3_f32 v200, v200, v70, v71
	v_mfma_f32_32x32x16_bf16 v[32:47], v[208:211], v[224:227], v[32:47]
	ds_read_b64_tr_b16 v[224:225], v165 offset:4608
	ds_read_b64_tr_b16 v[226:227], v165 offset:6656
	v_max3_f32 v200, v200, v72, v73
	v_max3_f32 v200, v200, v74, v75
	v_max3_f32 v200, v200, v76, v77
	v_max3_f32 v200, v200, v78, v79
	v_max3_f32 v200, v200, v80, v81
	v_mfma_f32_32x32x16_bf16 v[32:47], v[212:215], v[228:231], v[32:47]
	ds_read_b64_tr_b16 v[228:229], v165 offset:8704
	ds_read_b64_tr_b16 v[230:231], v165 offset:10752
	v_max3_f32 v200, v200, v82, v83
	v_max3_f32 v200, v200, v84, v85
	v_max3_f32 v200, v200, v86, v87
	v_max3_f32 v200, v200, v88, v89
	v_mfma_f32_32x32x16_bf16 v[32:47], v[216:219], v[232:235], v[32:47]
	ds_read_b64_tr_b16 v[232:233], v165 offset:12800
	ds_read_b64_tr_b16 v[234:235], v165 offset:14848
	v_max3_f32 v200, v200, v90, v91
	v_max3_f32 v200, v200, v92, v93
	v_max3_f32 v200, v200, v94, v95
	v_mov_b32_e32 v201, v200
	s_nop 1
	s_waitcnt lgkmcnt(0)
	v_mfma_f32_32x32x16_bf16 v[48:63], v[204:207], v[220:223], v[48:63]
	ds_read_b64_tr_b16 v[220:221], v165 offset:1024
	ds_read_b64_tr_b16 v[222:223], v165 offset:3072
	v_permlane32_swap_b32_e32 v200, v201
	v_max_f32_e32 v201, v201, v201
	v_max_f32_e32 v200, v200, v200
	v_max_f32_e32 v200, v200, v201
	v_sub_f32_e32 v201, v200, v203
	v_mfma_f32_32x32x16_bf16 v[48:63], v[208:211], v[224:227], v[48:63]
	ds_read_b64_tr_b16 v[224:225], v165 offset:5120
	ds_read_b64_tr_b16 v[226:227], v165 offset:7168
	v_mul_f32_e32 v201, 0x3db504f3, v201
	v_cmp_ge_f32_e32 vcc, 0x41000000, v201
	v_max_f32_e32 v201, v203, v203
	v_max_f32_e32 v200, v201, v200
	v_mfma_f32_32x32x16_bf16 v[48:63], v[212:215], v[228:231], v[48:63]
	ds_read_b64_tr_b16 v[228:229], v165 offset:9216
	ds_read_b64_tr_b16 v[230:231], v165 offset:11264
	v_sub_f32_e32 v201, v203, v200
	v_mul_f32_e32 v201, 0x3e0293ee, v201
	v_exp_f32_e32 v201, v201
	s_cmp_eq_u64 vcc, exec
	s_cselect_b64 s[44:45], -1, 0
	v_mfma_f32_32x32x16_bf16 v[48:63], v[216:219], v[232:235], v[48:63]
	ds_read_b64_tr_b16 v[232:233], v165 offset:13312
	ds_read_b64_tr_b16 v[234:235], v165 offset:15360
	v_cndmask_b32_e64 v202, v201, 1.0, s[44:45]
	v_cndmask_b32_e64 v203, v200, v203, s[44:45]
	v_mul_f32_e32 v248, 0xbe0293ee, v203
	v_pk_fma_f32 v[64:65], v[64:65], s[10:11], v[248:249] op_sel_hi:[1,0,0]
	v_pk_fma_f32 v[66:67], v[66:67], s[10:11], v[248:249] op_sel_hi:[1,0,0]
	s_waitcnt lgkmcnt(0)
	v_mfma_f32_32x32x16_bf16 v[16:31], v[204:207], v[220:223], v[16:31]
	ds_read_b64_tr_b16 v[220:221], v165 offset:1536
	ds_read_b64_tr_b16 v[222:223], v165 offset:3584
	v_pk_fma_f32 v[68:69], v[68:69], s[10:11], v[248:249] op_sel_hi:[1,0,0]
	v_pk_fma_f32 v[70:71], v[70:71], s[10:11], v[248:249] op_sel_hi:[1,0,0]
	v_pk_fma_f32 v[72:73], v[72:73], s[10:11], v[248:249] op_sel_hi:[1,0,0]
	v_pk_fma_f32 v[74:75], v[74:75], s[10:11], v[248:249] op_sel_hi:[1,0,0]
	v_mfma_f32_32x32x16_bf16 v[16:31], v[208:211], v[224:227], v[16:31]
	ds_read_b64_tr_b16 v[224:225], v165 offset:5632
	ds_read_b64_tr_b16 v[226:227], v165 offset:7680
	v_pk_fma_f32 v[76:77], v[76:77], s[10:11], v[248:249] op_sel_hi:[1,0,0]
	v_pk_fma_f32 v[78:79], v[78:79], s[10:11], v[248:249] op_sel_hi:[1,0,0]
	v_pk_fma_f32 v[80:81], v[80:81], s[10:11], v[248:249] op_sel_hi:[1,0,0]
	v_pk_fma_f32 v[82:83], v[82:83], s[10:11], v[248:249] op_sel_hi:[1,0,0]
	v_pk_fma_f32 v[84:85], v[84:85], s[10:11], v[248:249] op_sel_hi:[1,0,0]
	v_mfma_f32_32x32x16_bf16 v[16:31], v[212:215], v[228:231], v[16:31]
	ds_read_b64_tr_b16 v[228:229], v165 offset:9728
	ds_read_b64_tr_b16 v[230:231], v165 offset:11776
	v_pk_fma_f32 v[86:87], v[86:87], s[10:11], v[248:249] op_sel_hi:[1,0,0]
	v_pk_fma_f32 v[88:89], v[88:89], s[10:11], v[248:249] op_sel_hi:[1,0,0]
	v_pk_fma_f32 v[90:91], v[90:91], s[10:11], v[248:249] op_sel_hi:[1,0,0]
	v_pk_fma_f32 v[92:93], v[92:93], s[10:11], v[248:249] op_sel_hi:[1,0,0]
	v_pk_fma_f32 v[94:95], v[94:95], s[10:11], v[248:249] op_sel_hi:[1,0,0]
	v_mfma_f32_32x32x16_bf16 v[16:31], v[216:219], v[232:235], v[16:31]
	ds_read_b64_tr_b16 v[232:233], v165 offset:13824
	ds_read_b64_tr_b16 v[234:235], v165 offset:15872
	v_exp_f32_e32 v64, v64
	v_exp_f32_e32 v65, v65
	v_exp_f32_e32 v66, v66
	v_exp_f32_e32 v67, v67
	s_waitcnt lgkmcnt(0)
	v_mfma_f32_32x32x16_bf16 v[0:15], v[204:207], v[220:223], v[0:15]
	v_exp_f32_e32 v68, v68
	v_exp_f32_e32 v69, v69
	v_pk_add_f32 v[170:171], v[64:65], v[66:67]
	v_exp_f32_e32 v70, v70
	v_exp_f32_e32 v71, v71
	v_mfma_f32_32x32x16_bf16 v[0:15], v[208:211], v[224:227], v[0:15]
	v_pk_add_f32 v[170:171], v[170:171], v[68:69]
	v_exp_f32_e32 v72, v72
	v_exp_f32_e32 v73, v73
	v_pk_add_f32 v[170:171], v[170:171], v[70:71]
	v_exp_f32_e32 v74, v74
	v_mfma_f32_32x32x16_bf16 v[0:15], v[212:215], v[228:231], v[0:15]
	v_exp_f32_e32 v75, v75
	v_pk_add_f32 v[170:171], v[170:171], v[72:73]
	v_exp_f32_e32 v76, v76
	v_exp_f32_e32 v77, v77
	v_mfma_f32_32x32x16_bf16 v[0:15], v[216:219], v[232:235], v[0:15]
	v_pk_add_f32 v[170:171], v[170:171], v[74:75]
	v_exp_f32_e32 v78, v78
	v_exp_f32_e32 v79, v79
	v_pk_add_f32 v[170:171], v[170:171], v[76:77]
	v_cmp_gt_f32_e32 vcc, 1.0, v202
	s_cbranch_vccz .Lat_nre
	s_nop 7
	s_nop 7
	s_and_saveexec_b64 s[4:5], s[0:1]
	ds_write_b32 v183, v202
	s_or_b64 exec, exec, s[4:5]
	s_waitcnt lgkmcnt(0)
	ds_read_b128 v[244:247], v177 offset:0
	s_waitcnt lgkmcnt(0)
	v_pk_mul_f32 v[32:33], v[32:33], v[244:245]
	v_pk_mul_f32 v[34:35], v[34:35], v[246:247]
	v_pk_mul_f32 v[48:49], v[48:49], v[244:245]
	v_pk_mul_f32 v[50:51], v[50:51], v[246:247]
	v_pk_mul_f32 v[16:17], v[16:17], v[244:245]
	v_pk_mul_f32 v[18:19], v[18:19], v[246:247]
	v_pk_mul_f32 v[0:1], v[0:1], v[244:245]
	v_pk_mul_f32 v[2:3], v[2:3], v[246:247]
	ds_read_b128 v[244:247], v177 offset:32
	s_waitcnt lgkmcnt(0)
	v_pk_mul_f32 v[36:37], v[36:37], v[244:245]
	v_pk_mul_f32 v[38:39], v[38:39], v[246:247]
	v_pk_mul_f32 v[52:53], v[52:53], v[244:245]
	v_pk_mul_f32 v[54:55], v[54:55], v[246:247]
	v_pk_mul_f32 v[20:21], v[20:21], v[244:245]
	v_pk_mul_f32 v[22:23], v[22:23], v[246:247]
	v_pk_mul_f32 v[4:5], v[4:5], v[244:245]
	v_pk_mul_f32 v[6:7], v[6:7], v[246:247]
	ds_read_b128 v[244:247], v177 offset:64
	s_waitcnt lgkmcnt(0)
	v_pk_mul_f32 v[40:41], v[40:41], v[244:245]
	v_pk_mul_f32 v[42:43], v[42:43], v[246:247]
	v_pk_mul_f32 v[56:57], v[56:57], v[244:245]
	v_pk_mul_f32 v[58:59], v[58:59], v[246:247]
	v_pk_mul_f32 v[24:25], v[24:25], v[244:245]
	v_pk_mul_f32 v[26:27], v[26:27], v[246:247]
	v_pk_mul_f32 v[8:9], v[8:9], v[244:245]
	v_pk_mul_f32 v[10:11], v[10:11], v[246:247]
	ds_read_b128 v[244:247], v177 offset:96
	s_waitcnt lgkmcnt(0)
	v_pk_mul_f32 v[44:45], v[44:45], v[244:245]
	v_pk_mul_f32 v[46:47], v[46:47], v[246:247]
	v_pk_mul_f32 v[60:61], v[60:61], v[244:245]
	v_pk_mul_f32 v[62:63], v[62:63], v[246:247]
	v_pk_mul_f32 v[28:29], v[28:29], v[244:245]
	v_pk_mul_f32 v[30:31], v[30:31], v[246:247]
	v_pk_mul_f32 v[12:13], v[12:13], v[244:245]
	v_pk_mul_f32 v[14:15], v[14:15], v[246:247]
.Lat_nre:
	ds_read_b128 v[236:239], v186 offset:49152
	ds_read_b128 v[240:243], v186 offset:57344
	v_cvt_f32_u32_e32 v204, s13
	v_mov_b32_e32 v165, v164
	v_fma_f32 v204, v172, v204, v179
	v_add_f32_e32 v208, v173, v204
	v_add_f32_e32 v212, v173, v208
	v_add_f32_e32 v216, v173, v212
	v_add_f32_e32 v205, v172, v204
	v_add_f32_e32 v209, v172, v208
	v_add_f32_e32 v213, v172, v212
	v_add_f32_e32 v217, v172, v216
	v_pk_add_f32 v[206:207], v[162:163], v[204:205] op_sel_hi:[1,0]
	v_pk_add_f32 v[210:211], v[162:163], v[208:209] op_sel_hi:[1,0]
	v_pk_add_f32 v[214:215], v[162:163], v[212:213] op_sel_hi:[1,0]
	v_pk_add_f32 v[218:219], v[162:163], v[216:217] op_sel_hi:[1,0]
	v_pk_add_f32 v[222:223], v[164:165], v[206:207]
	v_pk_add_f32 v[220:221], v[166:167], v[204:205]
	v_pk_add_f32 v[226:227], v[164:165], v[210:211]
	v_pk_add_f32 v[224:225], v[164:165], v[208:209]
	v_pk_add_f32 v[230:231], v[164:165], v[214:215]
	v_pk_add_f32 v[228:229], v[164:165], v[212:213]
	v_pk_add_f32 v[234:235], v[164:165], v[218:219]
	v_pk_add_f32 v[232:233], v[164:165], v[216:217]
	s_addk_i32 s13, 0x40
	v_exp_f32_e32 v80, v80
	s_waitcnt lgkmcnt(1)
	v_mfma_f32_32x32x16_bf16 v[204:219], v[236:239], v[104:107], v[204:219]
	ds_read_b128 v[236:239], v187 offset:49152
	v_exp_f32_e32 v81, v81
	v_pk_add_f32 v[170:171], v[170:171], v[78:79]
	v_exp_f32_e32 v82, v82
	s_waitcnt lgkmcnt(1)
	v_mfma_f32_32x32x16_bf16 v[220:235], v[240:243], v[104:107], v[220:235]
	ds_read_b128 v[240:243], v187 offset:57344
	v_exp_f32_e32 v83, v83
	v_pk_add_f32 v[170:171], v[170:171], v[80:81]
	v_exp_f32_e32 v84, v84
	v_exp_f32_e32 v85, v85
	s_waitcnt lgkmcnt(1)
	v_mfma_f32_32x32x16_bf16 v[204:219], v[236:239], v[108:111], v[204:219]
	ds_read_b128 v[236:239], v188 offset:49152
	v_pk_add_f32 v[170:171], v[170:171], v[82:83]
	v_exp_f32_e32 v86, v86
	v_exp_f32_e32 v87, v87
	s_waitcnt lgkmcnt(1)
	v_mfma_f32_32x32x16_bf16 v[220:235], v[240:243], v[108:111], v[220:235]
	ds_read_b128 v[240:243], v188 offset:57344
	v_pk_add_f32 v[170:171], v[170:171], v[84:85]
	v_exp_f32_e32 v88, v88
	v_exp_f32_e32 v89, v89
	v_pk_add_f32 v[170:171], v[170:171], v[86:87]
	s_waitcnt lgkmcnt(1)
	v_mfma_f32_32x32x16_bf16 v[204:219], v[236:239], v[112:115], v[204:219]
	ds_read_b128 v[236:239], v189 offset:49152
	v_exp_f32_e32 v90, v90
	v_exp_f32_e32 v91, v91
	v_pk_add_f32 v[170:171], v[170:171], v[88:89]
	v_exp_f32_e32 v92, v92
	s_waitcnt lgkmcnt(1)
	v_mfma_f32_32x32x16_bf16 v[220:235], v[240:243], v[112:115], v[220:235]
	ds_read_b128 v[240:243], v189 offset:57344
	v_exp_f32_e32 v93, v93
	v_pk_add_f32 v[170:171], v[170:171], v[90:91]
	v_exp_f32_e32 v94, v94
	s_waitcnt lgkmcnt(1)
	v_mfma_f32_32x32x16_bf16 v[204:219], v[236:239], v[116:119], v[204:219]
	ds_read_b128 v[236:239], v186 offset:49280
	v_exp_f32_e32 v95, v95
	v_pk_add_f32 v[170:171], v[170:171], v[92:93]
	s_nop 0
	v_pk_add_f32 v[170:171], v[170:171], v[94:95]
	s_waitcnt lgkmcnt(1)
	v_mfma_f32_32x32x16_bf16 v[220:235], v[240:243], v[116:119], v[220:235]
	ds_read_b128 v[240:243], v186 offset:57472
	v_add_f32_e32 v249, v170, v171
	v_mov_b32_e32 v170, v249
	s_nop 1
	s_waitcnt lgkmcnt(1)
	v_mfma_f32_32x32x16_bf16 v[204:219], v[236:239], v[120:123], v[204:219]
	ds_read_b128 v[236:239], v187 offset:49280
	v_permlane32_swap_b32_e32 v249, v170
	v_cvt_pk_bf16_f32 v64, v64, v65
	v_cvt_pk_bf16_f32 v65, v66, v67
	v_cvt_pk_bf16_f32 v66, v68, v69
	s_waitcnt lgkmcnt(1)
	v_mfma_f32_32x32x16_bf16 v[220:235], v[240:243], v[120:123], v[220:235]
	ds_read_b128 v[240:243], v187 offset:57472
	v_cvt_pk_bf16_f32 v67, v70, v71
	v_cvt_pk_bf16_f32 v68, v72, v73
	v_cvt_pk_bf16_f32 v69, v74, v75
	s_waitcnt lgkmcnt(1)
	v_mfma_f32_32x32x16_bf16 v[204:219], v[236:239], v[124:127], v[204:219]
	ds_read_b128 v[236:239], v188 offset:49280
	v_cvt_pk_bf16_f32 v70, v76, v77
	v_cvt_pk_bf16_f32 v71, v78, v79
	v_cvt_pk_bf16_f32 v72, v80, v81
	v_cvt_pk_bf16_f32 v73, v82, v83
	s_waitcnt lgkmcnt(1)
	v_mfma_f32_32x32x16_bf16 v[220:235], v[240:243], v[124:127], v[220:235]
	ds_read_b128 v[240:243], v188 offset:57472
	v_cvt_pk_bf16_f32 v74, v84, v85
	v_cvt_pk_bf16_f32 v75, v86, v87
	v_cvt_pk_bf16_f32 v76, v88, v89
	s_waitcnt lgkmcnt(1)
	v_mfma_f32_32x32x16_bf16 v[204:219], v[236:239], v[128:131], v[204:219]
	ds_read_b128 v[236:239], v189 offset:49280
	v_cvt_pk_bf16_f32 v77, v90, v91
	v_cvt_pk_bf16_f32 v78, v92, v93
	v_cvt_pk_bf16_f32 v79, v94, v95
	v_permlane32_swap_b32_e32 v64, v66
	s_waitcnt lgkmcnt(1)
	v_mfma_f32_32x32x16_bf16 v[220:235], v[240:243], v[128:131], v[220:235]
	ds_read_b128 v[240:243], v189 offset:57472
	v_permlane32_swap_b32_e32 v65, v67
	v_permlane32_swap_b32_e32 v68, v70
	v_permlane32_swap_b32_e32 v69, v71
	v_permlane32_swap_b32_e32 v72, v74
	s_waitcnt lgkmcnt(1)
	v_mfma_f32_32x32x16_bf16 v[204:219], v[236:239], v[132:135], v[204:219]
	v_permlane32_swap_b32_e32 v73, v75
	v_permlane32_swap_b32_e32 v76, v78
	v_permlane32_swap_b32_e32 v77, v79
	s_waitcnt lgkmcnt(0)
	v_mfma_f32_32x32x16_bf16 v[220:235], v[240:243], v[132:135], v[220:235]
	v_add_f32_e32 v171, v249, v170
	v_fmac_f32_e32 v171, v185, v202
	v_mov_b32_e32 v185, v171
	s_waitcnt vmcnt(0)
	v_add_u32_e32 v200, s8, v180
	v_add_u32_e32 v201, s8, v181
	ds_write_b128 v200, v[96:99]
	ds_write_b128 v201, v[100:103]
	s_and_b64 vcc, exec, s[34:35]
	s_cbranch_vccz .Lat_nwe
	ds_write_b128 v182, v[136:139] offset:32768
	ds_write_b128 v182, v[140:143] offset:40960

.Lat_nmo:
	v_add_u32_e32 v184, 0xffffffc0, v184
	v_max_f32_e32 v200, v205, v205
	s_waitcnt lgkmcnt(0)
	v_mfma_f32_32x32x16_bf16 v[32:47], v[64:67], v[80:83], v[32:47]
	ds_read_b64_tr_b16 v[80:81], v165 offset:512
	ds_read_b64_tr_b16 v[82:83], v165 offset:2560
	v_max_f32_e32 v201, v204, v204
	v_max_f32_e32 v200, v201, v200
	v_max3_f32 v200, v200, v206, v207
	v_max3_f32 v200, v200, v208, v209
	v_max3_f32 v200, v200, v210, v211
	v_mfma_f32_32x32x16_bf16 v[32:47], v[68:71], v[84:87], v[32:47]
	ds_read_b64_tr_b16 v[84:85], v165 offset:4608
	ds_read_b64_tr_b16 v[86:87], v165 offset:6656
	v_max3_f32 v200, v200, v212, v213
	v_max3_f32 v200, v200, v214, v215
	v_max3_f32 v200, v200, v216, v217
	v_max3_f32 v200, v200, v218, v219
	v_max3_f32 v200, v200, v220, v221
	v_mfma_f32_32x32x16_bf16 v[32:47], v[72:75], v[88:91], v[32:47]
	ds_read_b64_tr_b16 v[88:89], v165 offset:8704
	ds_read_b64_tr_b16 v[90:91], v165 offset:10752
	v_max3_f32 v200, v200, v222, v223
	v_max3_f32 v200, v200, v224, v225
	v_max3_f32 v200, v200, v226, v227
	v_max3_f32 v200, v200, v228, v229
	v_mfma_f32_32x32x16_bf16 v[32:47], v[76:79], v[92:95], v[32:47]
	ds_read_b64_tr_b16 v[92:93], v165 offset:12800
	ds_read_b64_tr_b16 v[94:95], v165 offset:14848
	v_max3_f32 v200, v200, v230, v231
	v_max3_f32 v200, v200, v232, v233
	v_max3_f32 v200, v200, v234, v235
	v_mov_b32_e32 v201, v200
	s_nop 1
	s_waitcnt lgkmcnt(0)
	v_mfma_f32_32x32x16_bf16 v[48:63], v[64:67], v[80:83], v[48:63]
	ds_read_b64_tr_b16 v[80:81], v165 offset:1024
	ds_read_b64_tr_b16 v[82:83], v165 offset:3072
	v_permlane32_swap_b32_e32 v200, v201
	v_max_f32_e32 v201, v201, v201
	v_max_f32_e32 v200, v200, v200
	v_max_f32_e32 v200, v200, v201
	v_sub_f32_e32 v201, v200, v203
	v_mfma_f32_32x32x16_bf16 v[48:63], v[68:71], v[84:87], v[48:63]
	ds_read_b64_tr_b16 v[84:85], v165 offset:5120
	ds_read_b64_tr_b16 v[86:87], v165 offset:7168
	v_mul_f32_e32 v201, 0x3db504f3, v201
	v_cmp_ge_f32_e32 vcc, 0x41000000, v201
	v_max_f32_e32 v201, v203, v203
	v_max_f32_e32 v200, v201, v200
	v_mfma_f32_32x32x16_bf16 v[48:63], v[72:75], v[88:91], v[48:63]
	ds_read_b64_tr_b16 v[88:89], v165 offset:9216
	ds_read_b64_tr_b16 v[90:91], v165 offset:11264
	v_sub_f32_e32 v201, v203, v200
	v_mul_f32_e32 v201, 0x3e0293ee, v201
	v_exp_f32_e32 v201, v201
	s_cmp_eq_u64 vcc, exec
	s_cselect_b64 s[44:45], -1, 0
	v_mfma_f32_32x32x16_bf16 v[48:63], v[76:79], v[92:95], v[48:63]
	ds_read_b64_tr_b16 v[92:93], v165 offset:13312
	ds_read_b64_tr_b16 v[94:95], v165 offset:15360
	v_cndmask_b32_e64 v202, v201, 1.0, s[44:45]
	v_cndmask_b32_e64 v203, v200, v203, s[44:45]
	v_mul_f32_e32 v248, 0xbe0293ee, v203
	v_pk_fma_f32 v[204:205], v[204:205], s[10:11], v[248:249] op_sel_hi:[1,0,0]
	v_pk_fma_f32 v[206:207], v[206:207], s[10:11], v[248:249] op_sel_hi:[1,0,0]
	s_waitcnt lgkmcnt(0)
	v_mfma_f32_32x32x16_bf16 v[16:31], v[64:67], v[80:83], v[16:31]
	ds_read_b64_tr_b16 v[80:81], v165 offset:1536
	ds_read_b64_tr_b16 v[82:83], v165 offset:3584
	v_pk_fma_f32 v[208:209], v[208:209], s[10:11], v[248:249] op_sel_hi:[1,0,0]
	v_pk_fma_f32 v[210:211], v[210:211], s[10:11], v[248:249] op_sel_hi:[1,0,0]
	v_pk_fma_f32 v[212:213], v[212:213], s[10:11], v[248:249] op_sel_hi:[1,0,0]
	v_pk_fma_f32 v[214:215], v[214:215], s[10:11], v[248:249] op_sel_hi:[1,0,0]
	v_mfma_f32_32x32x16_bf16 v[16:31], v[68:71], v[84:87], v[16:31]
	ds_read_b64_tr_b16 v[84:85], v165 offset:5632
	ds_read_b64_tr_b16 v[86:87], v165 offset:7680
	v_pk_fma_f32 v[216:217], v[216:217], s[10:11], v[248:249] op_sel_hi:[1,0,0]
	v_pk_fma_f32 v[218:219], v[218:219], s[10:11], v[248:249] op_sel_hi:[1,0,0]
	v_pk_fma_f32 v[220:221], v[220:221], s[10:11], v[248:249] op_sel_hi:[1,0,0]
	v_pk_fma_f32 v[222:223], v[222:223], s[10:11], v[248:249] op_sel_hi:[1,0,0]
	v_pk_fma_f32 v[224:225], v[224:225], s[10:11], v[248:249] op_sel_hi:[1,0,0]
	v_mfma_f32_32x32x16_bf16 v[16:31], v[72:75], v[88:91], v[16:31]
	ds_read_b64_tr_b16 v[88:89], v165 offset:9728
	ds_read_b64_tr_b16 v[90:91], v165 offset:11776
	v_pk_fma_f32 v[226:227], v[226:227], s[10:11], v[248:249] op_sel_hi:[1,0,0]
	v_pk_fma_f32 v[228:229], v[228:229], s[10:11], v[248:249] op_sel_hi:[1,0,0]
	v_pk_fma_f32 v[230:231], v[230:231], s[10:11], v[248:249] op_sel_hi:[1,0,0]
	v_pk_fma_f32 v[232:233], v[232:233], s[10:11], v[248:249] op_sel_hi:[1,0,0]
	v_pk_fma_f32 v[234:235], v[234:235], s[10:11], v[248:249] op_sel_hi:[1,0,0]
	v_mfma_f32_32x32x16_bf16 v[16:31], v[76:79], v[92:95], v[16:31]
	ds_read_b64_tr_b16 v[92:93], v165 offset:13824
	ds_read_b64_tr_b16 v[94:95], v165 offset:15872
	v_exp_f32_e32 v204, v204
	v_exp_f32_e32 v205, v205
	v_exp_f32_e32 v206, v206
	v_exp_f32_e32 v207, v207
	s_waitcnt lgkmcnt(0)
	v_mfma_f32_32x32x16_bf16 v[0:15], v[64:67], v[80:83], v[0:15]
	v_exp_f32_e32 v208, v208
	v_exp_f32_e32 v209, v209
	v_pk_add_f32 v[170:171], v[204:205], v[206:207]
	v_exp_f32_e32 v210, v210
	v_exp_f32_e32 v211, v211
	v_mfma_f32_32x32x16_bf16 v[0:15], v[68:71], v[84:87], v[0:15]
	v_pk_add_f32 v[170:171], v[170:171], v[208:209]
	v_exp_f32_e32 v212, v212
	v_exp_f32_e32 v213, v213
	v_pk_add_f32 v[170:171], v[170:171], v[210:211]
	v_exp_f32_e32 v214, v214
	v_mfma_f32_32x32x16_bf16 v[0:15], v[72:75], v[88:91], v[0:15]
	v_exp_f32_e32 v215, v215
	v_pk_add_f32 v[170:171], v[170:171], v[212:213]
	v_exp_f32_e32 v216, v216
	v_exp_f32_e32 v217, v217
	v_mfma_f32_32x32x16_bf16 v[0:15], v[76:79], v[92:95], v[0:15]
	v_pk_add_f32 v[170:171], v[170:171], v[214:215]
	v_exp_f32_e32 v218, v218
	v_exp_f32_e32 v219, v219
	v_pk_add_f32 v[170:171], v[170:171], v[216:217]
	v_cmp_gt_f32_e32 vcc, 1.0, v202
	s_cbranch_vccz .Lat_nro
	s_nop 7
	s_nop 7
	s_and_saveexec_b64 s[4:5], s[0:1]
	ds_write_b32 v183, v202
	s_or_b64 exec, exec, s[4:5]
	s_waitcnt lgkmcnt(0)
	ds_read_b128 v[244:247], v177 offset:0
	s_waitcnt lgkmcnt(0)
	v_pk_mul_f32 v[32:33], v[32:33], v[244:245]
	v_pk_mul_f32 v[34:35], v[34:35], v[246:247]
	v_pk_mul_f32 v[48:49], v[48:49], v[244:245]
	v_pk_mul_f32 v[50:51], v[50:51], v[246:247]
	v_pk_mul_f32 v[16:17], v[16:17], v[244:245]
	v_pk_mul_f32 v[18:19], v[18:19], v[246:247]
	v_pk_mul_f32 v[0:1], v[0:1], v[244:245]
	v_pk_mul_f32 v[2:3], v[2:3], v[246:247]
	ds_read_b128 v[244:247], v177 offset:32
	s_waitcnt lgkmcnt(0)
	v_pk_mul_f32 v[36:37], v[36:37], v[244:245]
	v_pk_mul_f32 v[38:39], v[38:39], v[246:247]
	v_pk_mul_f32 v[52:53], v[52:53], v[244:245]
	v_pk_mul_f32 v[54:55], v[54:55], v[246:247]
	v_pk_mul_f32 v[20:21], v[20:21], v[244:245]
	v_pk_mul_f32 v[22:23], v[22:23], v[246:247]
	v_pk_mul_f32 v[4:5], v[4:5], v[244:245]
	v_pk_mul_f32 v[6:7], v[6:7], v[246:247]
	ds_read_b128 v[244:247], v177 offset:64
	s_waitcnt lgkmcnt(0)
	v_pk_mul_f32 v[40:41], v[40:41], v[244:245]
	v_pk_mul_f32 v[42:43], v[42:43], v[246:247]
	v_pk_mul_f32 v[56:57], v[56:57], v[244:245]
	v_pk_mul_f32 v[58:59], v[58:59], v[246:247]
	v_pk_mul_f32 v[24:25], v[24:25], v[244:245]
	v_pk_mul_f32 v[26:27], v[26:27], v[246:247]
	v_pk_mul_f32 v[8:9], v[8:9], v[244:245]
	v_pk_mul_f32 v[10:11], v[10:11], v[246:247]
	ds_read_b128 v[244:247], v177 offset:96
	s_waitcnt lgkmcnt(0)
	v_pk_mul_f32 v[44:45], v[44:45], v[244:245]
	v_pk_mul_f32 v[46:47], v[46:47], v[246:247]
	v_pk_mul_f32 v[60:61], v[60:61], v[244:245]
	v_pk_mul_f32 v[62:63], v[62:63], v[246:247]
	v_pk_mul_f32 v[28:29], v[28:29], v[244:245]
	v_pk_mul_f32 v[30:31], v[30:31], v[246:247]
	v_pk_mul_f32 v[12:13], v[12:13], v[244:245]
	v_pk_mul_f32 v[14:15], v[14:15], v[246:247]
.Lat_nro:
	ds_read_b128 v[236:239], v186 offset:32768
	ds_read_b128 v[240:243], v186 offset:40960
	v_cvt_f32_u32_e32 v64, s13
	v_mov_b32_e32 v165, v164
	v_fma_f32 v64, v172, v64, v179
	v_add_f32_e32 v68, v173, v64
	v_add_f32_e32 v72, v173, v68
	v_add_f32_e32 v76, v173, v72
	v_add_f32_e32 v65, v172, v64
	v_add_f32_e32 v69, v172, v68
	v_add_f32_e32 v73, v172, v72
	v_add_f32_e32 v77, v172, v76
	v_pk_add_f32 v[66:67], v[162:163], v[64:65] op_sel_hi:[1,0]
	v_pk_add_f32 v[70:71], v[162:163], v[68:69] op_sel_hi:[1,0]
	v_pk_add_f32 v[74:75], v[162:163], v[72:73] op_sel_hi:[1,0]
	v_pk_add_f32 v[78:79], v[162:163], v[76:77] op_sel_hi:[1,0]
	v_pk_add_f32 v[82:83], v[164:165], v[66:67]
	v_pk_add_f32 v[80:81], v[166:167], v[64:65]
	v_pk_add_f32 v[86:87], v[164:165], v[70:71]
	v_pk_add_f32 v[84:85], v[164:165], v[68:69]
	v_pk_add_f32 v[90:91], v[164:165], v[74:75]
	v_pk_add_f32 v[88:89], v[164:165], v[72:73]
	v_pk_add_f32 v[94:95], v[164:165], v[78:79]
	v_pk_add_f32 v[92:93], v[164:165], v[76:77]
	s_addk_i32 s13, 0x40
	v_exp_f32_e32 v220, v220
	s_waitcnt lgkmcnt(1)
	v_mfma_f32_32x32x16_bf16 v[64:79], v[236:239], v[104:107], v[64:79]
	ds_read_b128 v[236:239], v187 offset:32768
	v_exp_f32_e32 v221, v221
	v_pk_add_f32 v[170:171], v[170:171], v[218:219]
	v_exp_f32_e32 v222, v222
	s_waitcnt lgkmcnt(1)
	v_mfma_f32_32x32x16_bf16 v[80:95], v[240:243], v[104:107], v[80:95]
	ds_read_b128 v[240:243], v187 offset:40960
	v_exp_f32_e32 v223, v223
	v_pk_add_f32 v[170:171], v[170:171], v[220:221]
	v_exp_f32_e32 v224, v224
	v_exp_f32_e32 v225, v225
	s_waitcnt lgkmcnt(1)
	v_mfma_f32_32x32x16_bf16 v[64:79], v[236:239], v[108:111], v[64:79]
	ds_read_b128 v[236:239], v188 offset:32768
	v_pk_add_f32 v[170:171], v[170:171], v[222:223]
	v_exp_f32_e32 v226, v226
	v_exp_f32_e32 v227, v227
	s_waitcnt lgkmcnt(1)
	v_mfma_f32_32x32x16_bf16 v[80:95], v[240:243], v[108:111], v[80:95]
	ds_read_b128 v[240:243], v188 offset:40960
	v_pk_add_f32 v[170:171], v[170:171], v[224:225]
	v_exp_f32_e32 v228, v228
	v_exp_f32_e32 v229, v229
	v_pk_add_f32 v[170:171], v[170:171], v[226:227]
	s_waitcnt lgkmcnt(1)
	v_mfma_f32_32x32x16_bf16 v[64:79], v[236:239], v[112:115], v[64:79]
	ds_read_b128 v[236:239], v189 offset:32768
	v_exp_f32_e32 v230, v230
	v_exp_f32_e32 v231, v231
	v_pk_add_f32 v[170:171], v[170:171], v[228:229]
	v_exp_f32_e32 v232, v232
	s_waitcnt lgkmcnt(1)
	v_mfma_f32_32x32x16_bf16 v[80:95], v[240:243], v[112:115], v[80:95]
	ds_read_b128 v[240:243], v189 offset:40960
	v_exp_f32_e32 v233, v233
	v_pk_add_f32 v[170:171], v[170:171], v[230:231]
	v_exp_f32_e32 v234, v234
	s_waitcnt lgkmcnt(1)
	v_mfma_f32_32x32x16_bf16 v[64:79], v[236:239], v[116:119], v[64:79]
	ds_read_b128 v[236:239], v186 offset:32896
	v_exp_f32_e32 v235, v235
	v_pk_add_f32 v[170:171], v[170:171], v[232:233]
	s_nop 0
	v_pk_add_f32 v[170:171], v[170:171], v[234:235]
	s_waitcnt lgkmcnt(1)
	v_mfma_f32_32x32x16_bf16 v[80:95], v[240:243], v[116:119], v[80:95]
	ds_read_b128 v[240:243], v186 offset:41088
	v_add_f32_e32 v249, v170, v171
	v_mov_b32_e32 v170, v249
	s_nop 1
	s_waitcnt lgkmcnt(1)
	v_mfma_f32_32x32x16_bf16 v[64:79], v[236:239], v[120:123], v[64:79]
	ds_read_b128 v[236:239], v187 offset:32896
	v_permlane32_swap_b32_e32 v249, v170
	v_cvt_pk_bf16_f32 v204, v204, v205
	v_cvt_pk_bf16_f32 v205, v206, v207
	v_cvt_pk_bf16_f32 v206, v208, v209
	s_waitcnt lgkmcnt(1)
	v_mfma_f32_32x32x16_bf16 v[80:95], v[240:243], v[120:123], v[80:95]
	ds_read_b128 v[240:243], v187 offset:41088
	v_cvt_pk_bf16_f32 v207, v210, v211
	v_cvt_pk_bf16_f32 v208, v212, v213
	v_cvt_pk_bf16_f32 v209, v214, v215
	s_waitcnt lgkmcnt(1)
	v_mfma_f32_32x32x16_bf16 v[64:79], v[236:239], v[124:127], v[64:79]
	ds_read_b128 v[236:239], v188 offset:32896
	v_cvt_pk_bf16_f32 v210, v216, v217
	v_cvt_pk_bf16_f32 v211, v218, v219
	v_cvt_pk_bf16_f32 v212, v220, v221
	v_cvt_pk_bf16_f32 v213, v222, v223
	s_waitcnt lgkmcnt(1)
	v_mfma_f32_32x32x16_bf16 v[80:95], v[240:243], v[124:127], v[80:95]
	ds_read_b128 v[240:243], v188 offset:41088
	v_cvt_pk_bf16_f32 v214, v224, v225
	v_cvt_pk_bf16_f32 v215, v226, v227
	v_cvt_pk_bf16_f32 v216, v228, v229
	s_waitcnt lgkmcnt(1)
	v_mfma_f32_32x32x16_bf16 v[64:79], v[236:239], v[128:131], v[64:79]
	ds_read_b128 v[236:239], v189 offset:32896
	v_cvt_pk_bf16_f32 v217, v230, v231
	v_cvt_pk_bf16_f32 v218, v232, v233
	v_cvt_pk_bf16_f32 v219, v234, v235
	v_permlane32_swap_b32_e32 v204, v206
	s_waitcnt lgkmcnt(1)
	v_mfma_f32_32x32x16_bf16 v[80:95], v[240:243], v[128:131], v[80:95]
	ds_read_b128 v[240:243], v189 offset:41088
	v_permlane32_swap_b32_e32 v205, v207
	v_permlane32_swap_b32_e32 v208, v210
	v_permlane32_swap_b32_e32 v209, v211
	v_permlane32_swap_b32_e32 v212, v214
	s_waitcnt lgkmcnt(1)
	v_mfma_f32_32x32x16_bf16 v[64:79], v[236:239], v[132:135], v[64:79]
	v_permlane32_swap_b32_e32 v213, v215
	v_permlane32_swap_b32_e32 v216, v218
	v_permlane32_swap_b32_e32 v217, v219
	s_waitcnt lgkmcnt(0)
	v_mfma_f32_32x32x16_bf16 v[80:95], v[240:243], v[132:135], v[80:95]
	v_add_f32_e32 v171, v249, v170
	v_fmac_f32_e32 v171, v185, v202
	v_mov_b32_e32 v185, v171
	s_waitcnt vmcnt(0)
	s_and_b64 vcc, exec, s[34:35]
	s_cbranch_vccz .Lat_nwo
	v_add_u32_e32 v200, s8, v180
	v_add_u32_e32 v201, s8, v181
	ds_write_b128 v200, v[96:99]
	ds_write_b128 v201, v[100:103]
	ds_write_b128 v182, v[136:139] offset:49152
	ds_write_b128 v182, v[140:143] offset:57344
